# combo1 + hand-written GLU-GEMM epilogue with all operand loads of a half tile in flight
# speedup vs baseline: 1.0146x; 1.0015x over previous
.LBB0_726:
	s_andn2_b64 vcc, exec, s[0:1]
	s_mov_b64 s[0:1], -1
	v_and_b32_e32 v160, 63, v234
	v_lshrrev_b32_e32 v161, 6, v234
	v_and_b32_e32 v162, 15, v160
	v_lshrrev_b32_e32 v160, 4, v160
	v_lshrrev_b32_e32 v163, 2, v161
	v_and_b32_e32 v161, 3, v161
	v_lshl_add_u32 v162, v163, 6, v162
	v_lshlrev_b32_e32 v161, 5, v161
	v_lshl_add_u32 v161, v160, 3, v161
	v_lshlrev_b32_e32 v254, 11, v162
	v_lshl_add_u32 v254, v161, 1, v254
	v_lshlrev_b32_e32 v255, 12, v162
	v_lshl_add_u32 v255, v161, 1, v255
	v_lshlrev_b32_e32 v163, 2, v161
	s_lshl_b32 s53, s38, 19
	s_lshl_b32 s54, s2, 9
	s_add_u32 s53, s53, s54
	s_add_u32 s40, s20, s53
	s_addc_u32 s41, s21, 0
	s_add_u32 s42, s10, s53
	s_addc_u32 s43, s11, 0
	s_add_u32 s66, s40, 0x40000
	s_addc_u32 s67, s41, 0
	s_add_u32 s68, s42, 0x40000
	s_addc_u32 s69, s43, 0
	s_lshl_b32 s53, s38, 20
	s_add_u32 s53, s53, s54
	s_add_u32 s53, s53, 0x800
	s_add_u32 s44, s6, s53
	s_addc_u32 s45, s7, 0
	s_add_u32 s70, s44, 0x80000
	s_addc_u32 s71, s45, 0
	s_lshl_b32 s54, s2, 10
	s_add_u32 s56, s64, s54
	s_addc_u32 s57, s65, 0
	global_load_dwordx4 v[40:43], v163, s[56:57]
	global_load_dwordx4 v[44:47], v163, s[56:57] offset:16
	global_load_dwordx4 v[64:67], v163, s[56:57] offset:512
	global_load_dwordx4 v[68:71], v163, s[56:57] offset:528
	global_load_dwordx4 v[170:173], v254, s[40:41]
	global_load_dwordx4 v[174:177], v254, s[42:43]
	global_load_dwordx4 v[178:181], v254, s[40:41] offset:256
	global_load_dwordx4 v[182:185], v254, s[42:43] offset:256
	s_add_u32 s40, s40, 0x8000
	s_addc_u32 s41, s41, 0
	s_add_u32 s42, s42, 0x8000
	s_addc_u32 s43, s43, 0
	global_load_dwordx4 v[186:189], v254, s[40:41]
	global_load_dwordx4 v[190:193], v254, s[42:43]
	global_load_dwordx4 v[194:197], v254, s[40:41] offset:256
	global_load_dwordx4 v[198:201], v254, s[42:43] offset:256
	s_add_u32 s40, s40, 0x8000
	s_addc_u32 s41, s41, 0
	s_add_u32 s42, s42, 0x8000
	s_addc_u32 s43, s43, 0
	global_load_dwordx4 v[202:205], v254, s[40:41]
	global_load_dwordx4 v[206:209], v254, s[42:43]
	global_load_dwordx4 v[210:213], v254, s[40:41] offset:256
	global_load_dwordx4 v[214:217], v254, s[42:43] offset:256
	s_add_u32 s40, s40, 0x8000
	s_addc_u32 s41, s41, 0
	s_add_u32 s42, s42, 0x8000
	s_addc_u32 s43, s43, 0
	global_load_dwordx4 v[218:221], v254, s[40:41]
	global_load_dwordx4 v[222:225], v254, s[42:43]
	global_load_dwordx4 v[226:229], v254, s[40:41] offset:256
	global_load_dwordx4 v[230:233], v254, s[42:43] offset:256
	v_add_f32_e32 v140, v140, v40
	v_add_f32_e32 v141, v141, v41
	v_add_f32_e32 v142, v142, v42
	v_add_f32_e32 v143, v143, v43
	v_add_f32_e32 v136, v136, v44
	v_add_f32_e32 v137, v137, v45
	v_add_f32_e32 v138, v138, v46
	v_add_f32_e32 v139, v139, v47
	v_mul_f32_e32 v235, 0xbfb8aa3b, v140
	v_mul_f32_e32 v236, 0xbfb8aa3b, v141
	v_mul_f32_e32 v237, 0xbfb8aa3b, v142
	v_mul_f32_e32 v238, 0xbfb8aa3b, v143
	v_mul_f32_e32 v239, 0xbfb8aa3b, v136
	v_mul_f32_e32 v240, 0xbfb8aa3b, v137
	v_mul_f32_e32 v241, 0xbfb8aa3b, v138
	v_mul_f32_e32 v242, 0xbfb8aa3b, v139
	v_exp_f32_e32 v235, v235
	v_exp_f32_e32 v236, v236
	v_exp_f32_e32 v237, v237
	v_exp_f32_e32 v238, v238
	v_exp_f32_e32 v239, v239
	v_exp_f32_e32 v240, v240
	v_exp_f32_e32 v241, v241
	v_exp_f32_e32 v242, v242
	v_add_f32_e32 v235, 1.0, v235
	v_add_f32_e32 v236, 1.0, v236
	v_add_f32_e32 v237, 1.0, v237
	v_add_f32_e32 v238, 1.0, v238
	v_add_f32_e32 v239, 1.0, v239
	v_add_f32_e32 v240, 1.0, v240
	v_add_f32_e32 v241, 1.0, v241
	v_add_f32_e32 v242, 1.0, v242
	v_rcp_f32_e32 v235, v235
	v_rcp_f32_e32 v236, v236
	v_rcp_f32_e32 v237, v237
	v_rcp_f32_e32 v238, v238
	v_rcp_f32_e32 v239, v239
	v_rcp_f32_e32 v240, v240
	v_rcp_f32_e32 v241, v241
	v_rcp_f32_e32 v242, v242
	s_waitcnt vmcnt(14)
	v_lshlrev_b32_e32 v160, 16, v170
	v_lshlrev_b32_e32 v161, 16, v174
	v_mul_f32_e32 v235, v235, v160
	v_mul_f32_e32 v235, v235, v161
	v_and_b32_e32 v160, 0xffff0000, v170
	v_and_b32_e32 v161, 0xffff0000, v174
	v_mul_f32_e32 v236, v236, v160
	v_mul_f32_e32 v236, v236, v161
	v_cvt_pk_bf16_f32 v244, v235, v236
	v_lshlrev_b32_e32 v160, 16, v171
	v_lshlrev_b32_e32 v161, 16, v175
	v_mul_f32_e32 v237, v237, v160
	v_mul_f32_e32 v237, v237, v161
	v_and_b32_e32 v160, 0xffff0000, v171
	v_and_b32_e32 v161, 0xffff0000, v175
	v_mul_f32_e32 v238, v238, v160
	v_mul_f32_e32 v238, v238, v161
	v_cvt_pk_bf16_f32 v245, v237, v238
	v_lshlrev_b32_e32 v160, 16, v172
	v_lshlrev_b32_e32 v161, 16, v176
	v_mul_f32_e32 v239, v239, v160
	v_mul_f32_e32 v239, v239, v161
	v_and_b32_e32 v160, 0xffff0000, v172
	v_and_b32_e32 v161, 0xffff0000, v176
	v_mul_f32_e32 v240, v240, v160
	v_mul_f32_e32 v240, v240, v161
	v_cvt_pk_bf16_f32 v246, v239, v240
	v_lshlrev_b32_e32 v160, 16, v173
	v_lshlrev_b32_e32 v161, 16, v177
	v_mul_f32_e32 v241, v241, v160
	v_mul_f32_e32 v241, v241, v161
	v_and_b32_e32 v160, 0xffff0000, v173
	v_and_b32_e32 v161, 0xffff0000, v177
	v_mul_f32_e32 v242, v242, v160
	v_mul_f32_e32 v242, v242, v161
	v_cvt_pk_bf16_f32 v247, v241, v242
	global_store_dwordx4 v255, v[244:247], s[44:45]
	global_load_dwordx4 v[140:143], v254, s[66:67]
	global_load_dwordx4 v[136:139], v254, s[68:69]
	v_add_f32_e32 v132, v132, v64
	v_add_f32_e32 v133, v133, v65
	v_add_f32_e32 v134, v134, v66
	v_add_f32_e32 v135, v135, v67
	v_add_f32_e32 v128, v128, v68
	v_add_f32_e32 v129, v129, v69
	v_add_f32_e32 v130, v130, v70
	v_add_f32_e32 v131, v131, v71
	v_mul_f32_e32 v235, 0xbfb8aa3b, v132
	v_mul_f32_e32 v236, 0xbfb8aa3b, v133
	v_mul_f32_e32 v237, 0xbfb8aa3b, v134
	v_mul_f32_e32 v238, 0xbfb8aa3b, v135
	v_mul_f32_e32 v239, 0xbfb8aa3b, v128
	v_mul_f32_e32 v240, 0xbfb8aa3b, v129
	v_mul_f32_e32 v241, 0xbfb8aa3b, v130
	v_mul_f32_e32 v242, 0xbfb8aa3b, v131
	v_exp_f32_e32 v235, v235
	v_exp_f32_e32 v236, v236
	v_exp_f32_e32 v237, v237
	v_exp_f32_e32 v238, v238
	v_exp_f32_e32 v239, v239
	v_exp_f32_e32 v240, v240
	v_exp_f32_e32 v241, v241
	v_exp_f32_e32 v242, v242
	v_add_f32_e32 v235, 1.0, v235
	v_add_f32_e32 v236, 1.0, v236
	v_add_f32_e32 v237, 1.0, v237
	v_add_f32_e32 v238, 1.0, v238
	v_add_f32_e32 v239, 1.0, v239
	v_add_f32_e32 v240, 1.0, v240
	v_add_f32_e32 v241, 1.0, v241
	v_add_f32_e32 v242, 1.0, v242
	v_rcp_f32_e32 v235, v235
	v_rcp_f32_e32 v236, v236
	v_rcp_f32_e32 v237, v237
	v_rcp_f32_e32 v238, v238
	v_rcp_f32_e32 v239, v239
	v_rcp_f32_e32 v240, v240
	v_rcp_f32_e32 v241, v241
	v_rcp_f32_e32 v242, v242
	s_waitcnt vmcnt(15)
	v_lshlrev_b32_e32 v160, 16, v178
	v_lshlrev_b32_e32 v161, 16, v182
	v_mul_f32_e32 v235, v235, v160
	v_mul_f32_e32 v235, v235, v161
	v_and_b32_e32 v160, 0xffff0000, v178
	v_and_b32_e32 v161, 0xffff0000, v182
	v_mul_f32_e32 v236, v236, v160
	v_mul_f32_e32 v236, v236, v161
	v_cvt_pk_bf16_f32 v248, v235, v236
	v_lshlrev_b32_e32 v160, 16, v179
	v_lshlrev_b32_e32 v161, 16, v183
	v_mul_f32_e32 v237, v237, v160
	v_mul_f32_e32 v237, v237, v161
	v_and_b32_e32 v160, 0xffff0000, v179
	v_and_b32_e32 v161, 0xffff0000, v183
	v_mul_f32_e32 v238, v238, v160
	v_mul_f32_e32 v238, v238, v161
	v_cvt_pk_bf16_f32 v249, v237, v238
	v_lshlrev_b32_e32 v160, 16, v180
	v_lshlrev_b32_e32 v161, 16, v184
	v_mul_f32_e32 v239, v239, v160
	v_mul_f32_e32 v239, v239, v161
	v_and_b32_e32 v160, 0xffff0000, v180
	v_and_b32_e32 v161, 0xffff0000, v184
	v_mul_f32_e32 v240, v240, v160
	v_mul_f32_e32 v240, v240, v161
	v_cvt_pk_bf16_f32 v250, v239, v240
	v_lshlrev_b32_e32 v160, 16, v181
	v_lshlrev_b32_e32 v161, 16, v185
	v_mul_f32_e32 v241, v241, v160
	v_mul_f32_e32 v241, v241, v161
	v_and_b32_e32 v160, 0xffff0000, v181
	v_and_b32_e32 v161, 0xffff0000, v185
	v_mul_f32_e32 v242, v242, v160
	v_mul_f32_e32 v242, v242, v161
	v_cvt_pk_bf16_f32 v251, v241, v242
	global_store_dwordx4 v255, v[248:251], s[44:45] offset:256
	s_add_u32 s44, s44, 0x10000
	s_addc_u32 s45, s45, 0
	global_load_dwordx4 v[132:135], v254, s[66:67] offset:256
	global_load_dwordx4 v[128:131], v254, s[68:69] offset:256
	s_add_u32 s66, s66, 0x8000
	s_addc_u32 s67, s67, 0
	s_add_u32 s68, s68, 0x8000
	s_addc_u32 s69, s69, 0
	v_add_f32_e32 v124, v124, v40
	v_add_f32_e32 v125, v125, v41
	v_add_f32_e32 v126, v126, v42
	v_add_f32_e32 v127, v127, v43
	v_add_f32_e32 v120, v120, v44
	v_add_f32_e32 v121, v121, v45
	v_add_f32_e32 v122, v122, v46
	v_add_f32_e32 v123, v123, v47
	v_mul_f32_e32 v235, 0xbfb8aa3b, v124
	v_mul_f32_e32 v236, 0xbfb8aa3b, v125
	v_mul_f32_e32 v237, 0xbfb8aa3b, v126
	v_mul_f32_e32 v238, 0xbfb8aa3b, v127
	v_mul_f32_e32 v239, 0xbfb8aa3b, v120
	v_mul_f32_e32 v240, 0xbfb8aa3b, v121
	v_mul_f32_e32 v241, 0xbfb8aa3b, v122
	v_mul_f32_e32 v242, 0xbfb8aa3b, v123
	v_exp_f32_e32 v235, v235
	v_exp_f32_e32 v236, v236
	v_exp_f32_e32 v237, v237
	v_exp_f32_e32 v238, v238
	v_exp_f32_e32 v239, v239
	v_exp_f32_e32 v240, v240
	v_exp_f32_e32 v241, v241
	v_exp_f32_e32 v242, v242
	v_add_f32_e32 v235, 1.0, v235
	v_add_f32_e32 v236, 1.0, v236
	v_add_f32_e32 v237, 1.0, v237
	v_add_f32_e32 v238, 1.0, v238
	v_add_f32_e32 v239, 1.0, v239
	v_add_f32_e32 v240, 1.0, v240
	v_add_f32_e32 v241, 1.0, v241
	v_add_f32_e32 v242, 1.0, v242
	v_rcp_f32_e32 v235, v235
	v_rcp_f32_e32 v236, v236
	v_rcp_f32_e32 v237, v237
	v_rcp_f32_e32 v238, v238
	v_rcp_f32_e32 v239, v239
	v_rcp_f32_e32 v240, v240
	v_rcp_f32_e32 v241, v241
	v_rcp_f32_e32 v242, v242
	s_waitcnt vmcnt(16)
	v_lshlrev_b32_e32 v160, 16, v186
	v_lshlrev_b32_e32 v161, 16, v190
	v_mul_f32_e32 v235, v235, v160
	v_mul_f32_e32 v235, v235, v161
	v_and_b32_e32 v160, 0xffff0000, v186
	v_and_b32_e32 v161, 0xffff0000, v190
	v_mul_f32_e32 v236, v236, v160
	v_mul_f32_e32 v236, v236, v161
	v_cvt_pk_bf16_f32 v244, v235, v236
	v_lshlrev_b32_e32 v160, 16, v187
	v_lshlrev_b32_e32 v161, 16, v191
	v_mul_f32_e32 v237, v237, v160
	v_mul_f32_e32 v237, v237, v161
	v_and_b32_e32 v160, 0xffff0000, v187
	v_and_b32_e32 v161, 0xffff0000, v191
	v_mul_f32_e32 v238, v238, v160
	v_mul_f32_e32 v238, v238, v161
	v_cvt_pk_bf16_f32 v245, v237, v238
	v_lshlrev_b32_e32 v160, 16, v188
	v_lshlrev_b32_e32 v161, 16, v192
	v_mul_f32_e32 v239, v239, v160
	v_mul_f32_e32 v239, v239, v161
	v_and_b32_e32 v160, 0xffff0000, v188
	v_and_b32_e32 v161, 0xffff0000, v192
	v_mul_f32_e32 v240, v240, v160
	v_mul_f32_e32 v240, v240, v161
	v_cvt_pk_bf16_f32 v246, v239, v240
	v_lshlrev_b32_e32 v160, 16, v189
	v_lshlrev_b32_e32 v161, 16, v193
	v_mul_f32_e32 v241, v241, v160
	v_mul_f32_e32 v241, v241, v161
	v_and_b32_e32 v160, 0xffff0000, v189
	v_and_b32_e32 v161, 0xffff0000, v193
	v_mul_f32_e32 v242, v242, v160
	v_mul_f32_e32 v242, v242, v161
	v_cvt_pk_bf16_f32 v247, v241, v242
	global_store_dwordx4 v255, v[244:247], s[44:45]
	global_load_dwordx4 v[124:127], v254, s[66:67]
	global_load_dwordx4 v[120:123], v254, s[68:69]
	v_add_f32_e32 v116, v116, v64
	v_add_f32_e32 v117, v117, v65
	v_add_f32_e32 v118, v118, v66
	v_add_f32_e32 v119, v119, v67
	v_add_f32_e32 v112, v112, v68
	v_add_f32_e32 v113, v113, v69
	v_add_f32_e32 v114, v114, v70
	v_add_f32_e32 v115, v115, v71
	v_mul_f32_e32 v235, 0xbfb8aa3b, v116
	v_mul_f32_e32 v236, 0xbfb8aa3b, v117
	v_mul_f32_e32 v237, 0xbfb8aa3b, v118
	v_mul_f32_e32 v238, 0xbfb8aa3b, v119
	v_mul_f32_e32 v239, 0xbfb8aa3b, v112
	v_mul_f32_e32 v240, 0xbfb8aa3b, v113
	v_mul_f32_e32 v241, 0xbfb8aa3b, v114
	v_mul_f32_e32 v242, 0xbfb8aa3b, v115
	v_exp_f32_e32 v235, v235
	v_exp_f32_e32 v236, v236
	v_exp_f32_e32 v237, v237
	v_exp_f32_e32 v238, v238
	v_exp_f32_e32 v239, v239
	v_exp_f32_e32 v240, v240
	v_exp_f32_e32 v241, v241
	v_exp_f32_e32 v242, v242
	v_add_f32_e32 v235, 1.0, v235
	v_add_f32_e32 v236, 1.0, v236
	v_add_f32_e32 v237, 1.0, v237
	v_add_f32_e32 v238, 1.0, v238
	v_add_f32_e32 v239, 1.0, v239
	v_add_f32_e32 v240, 1.0, v240
	v_add_f32_e32 v241, 1.0, v241
	v_add_f32_e32 v242, 1.0, v242
	v_rcp_f32_e32 v235, v235
	v_rcp_f32_e32 v236, v236
	v_rcp_f32_e32 v237, v237
	v_rcp_f32_e32 v238, v238
	v_rcp_f32_e32 v239, v239
	v_rcp_f32_e32 v240, v240
	v_rcp_f32_e32 v241, v241
	v_rcp_f32_e32 v242, v242
	s_waitcnt vmcnt(17)
	v_lshlrev_b32_e32 v160, 16, v194
	v_lshlrev_b32_e32 v161, 16, v198
	v_mul_f32_e32 v235, v235, v160
	v_mul_f32_e32 v235, v235, v161
	v_and_b32_e32 v160, 0xffff0000, v194
	v_and_b32_e32 v161, 0xffff0000, v198
	v_mul_f32_e32 v236, v236, v160
	v_mul_f32_e32 v236, v236, v161
	v_cvt_pk_bf16_f32 v248, v235, v236
	v_lshlrev_b32_e32 v160, 16, v195
	v_lshlrev_b32_e32 v161, 16, v199
	v_mul_f32_e32 v237, v237, v160
	v_mul_f32_e32 v237, v237, v161
	v_and_b32_e32 v160, 0xffff0000, v195
	v_and_b32_e32 v161, 0xffff0000, v199
	v_mul_f32_e32 v238, v238, v160
	v_mul_f32_e32 v238, v238, v161
	v_cvt_pk_bf16_f32 v249, v237, v238
	v_lshlrev_b32_e32 v160, 16, v196
	v_lshlrev_b32_e32 v161, 16, v200
	v_mul_f32_e32 v239, v239, v160
	v_mul_f32_e32 v239, v239, v161
	v_and_b32_e32 v160, 0xffff0000, v196
	v_and_b32_e32 v161, 0xffff0000, v200
	v_mul_f32_e32 v240, v240, v160
	v_mul_f32_e32 v240, v240, v161
	v_cvt_pk_bf16_f32 v250, v239, v240
	v_lshlrev_b32_e32 v160, 16, v197
	v_lshlrev_b32_e32 v161, 16, v201
	v_mul_f32_e32 v241, v241, v160
	v_mul_f32_e32 v241, v241, v161
	v_and_b32_e32 v160, 0xffff0000, v197
	v_and_b32_e32 v161, 0xffff0000, v201
	v_mul_f32_e32 v242, v242, v160
	v_mul_f32_e32 v242, v242, v161
	v_cvt_pk_bf16_f32 v251, v241, v242
	global_store_dwordx4 v255, v[248:251], s[44:45] offset:256
	s_add_u32 s44, s44, 0x10000
	s_addc_u32 s45, s45, 0
	global_load_dwordx4 v[116:119], v254, s[66:67] offset:256
	global_load_dwordx4 v[112:115], v254, s[68:69] offset:256
	s_add_u32 s66, s66, 0x8000
	s_addc_u32 s67, s67, 0
	s_add_u32 s68, s68, 0x8000
	s_addc_u32 s69, s69, 0
	v_add_f32_e32 v108, v108, v40
	v_add_f32_e32 v109, v109, v41
	v_add_f32_e32 v110, v110, v42
	v_add_f32_e32 v111, v111, v43
	v_add_f32_e32 v104, v104, v44
	v_add_f32_e32 v105, v105, v45
	v_add_f32_e32 v106, v106, v46
	v_add_f32_e32 v107, v107, v47
	v_mul_f32_e32 v235, 0xbfb8aa3b, v108
	v_mul_f32_e32 v236, 0xbfb8aa3b, v109
	v_mul_f32_e32 v237, 0xbfb8aa3b, v110
	v_mul_f32_e32 v238, 0xbfb8aa3b, v111
	v_mul_f32_e32 v239, 0xbfb8aa3b, v104
	v_mul_f32_e32 v240, 0xbfb8aa3b, v105
	v_mul_f32_e32 v241, 0xbfb8aa3b, v106
	v_mul_f32_e32 v242, 0xbfb8aa3b, v107
	v_exp_f32_e32 v235, v235
	v_exp_f32_e32 v236, v236
	v_exp_f32_e32 v237, v237
	v_exp_f32_e32 v238, v238
	v_exp_f32_e32 v239, v239
	v_exp_f32_e32 v240, v240
	v_exp_f32_e32 v241, v241
	v_exp_f32_e32 v242, v242
	v_add_f32_e32 v235, 1.0, v235
	v_add_f32_e32 v236, 1.0, v236
	v_add_f32_e32 v237, 1.0, v237
	v_add_f32_e32 v238, 1.0, v238
	v_add_f32_e32 v239, 1.0, v239
	v_add_f32_e32 v240, 1.0, v240
	v_add_f32_e32 v241, 1.0, v241
	v_add_f32_e32 v242, 1.0, v242
	v_rcp_f32_e32 v235, v235
	v_rcp_f32_e32 v236, v236
	v_rcp_f32_e32 v237, v237
	v_rcp_f32_e32 v238, v238
	v_rcp_f32_e32 v239, v239
	v_rcp_f32_e32 v240, v240
	v_rcp_f32_e32 v241, v241
	v_rcp_f32_e32 v242, v242
	s_waitcnt vmcnt(18)
	v_lshlrev_b32_e32 v160, 16, v202
	v_lshlrev_b32_e32 v161, 16, v206
	v_mul_f32_e32 v235, v235, v160
	v_mul_f32_e32 v235, v235, v161
	v_and_b32_e32 v160, 0xffff0000, v202
	v_and_b32_e32 v161, 0xffff0000, v206
	v_mul_f32_e32 v236, v236, v160
	v_mul_f32_e32 v236, v236, v161
	v_cvt_pk_bf16_f32 v244, v235, v236
	v_lshlrev_b32_e32 v160, 16, v203
	v_lshlrev_b32_e32 v161, 16, v207
	v_mul_f32_e32 v237, v237, v160
	v_mul_f32_e32 v237, v237, v161
	v_and_b32_e32 v160, 0xffff0000, v203
	v_and_b32_e32 v161, 0xffff0000, v207
	v_mul_f32_e32 v238, v238, v160
	v_mul_f32_e32 v238, v238, v161
	v_cvt_pk_bf16_f32 v245, v237, v238
	v_lshlrev_b32_e32 v160, 16, v204
	v_lshlrev_b32_e32 v161, 16, v208
	v_mul_f32_e32 v239, v239, v160
	v_mul_f32_e32 v239, v239, v161
	v_and_b32_e32 v160, 0xffff0000, v204
	v_and_b32_e32 v161, 0xffff0000, v208
	v_mul_f32_e32 v240, v240, v160
	v_mul_f32_e32 v240, v240, v161
	v_cvt_pk_bf16_f32 v246, v239, v240
	v_lshlrev_b32_e32 v160, 16, v205
	v_lshlrev_b32_e32 v161, 16, v209
	v_mul_f32_e32 v241, v241, v160
	v_mul_f32_e32 v241, v241, v161
	v_and_b32_e32 v160, 0xffff0000, v205
	v_and_b32_e32 v161, 0xffff0000, v209
	v_mul_f32_e32 v242, v242, v160
	v_mul_f32_e32 v242, v242, v161
	v_cvt_pk_bf16_f32 v247, v241, v242
	global_store_dwordx4 v255, v[244:247], s[44:45]
	global_load_dwordx4 v[108:111], v254, s[66:67]
	global_load_dwordx4 v[104:107], v254, s[68:69]
	v_add_f32_e32 v100, v100, v64
	v_add_f32_e32 v101, v101, v65
	v_add_f32_e32 v102, v102, v66
	v_add_f32_e32 v103, v103, v67
	v_add_f32_e32 v96, v96, v68
	v_add_f32_e32 v97, v97, v69
	v_add_f32_e32 v98, v98, v70
	v_add_f32_e32 v99, v99, v71
	v_mul_f32_e32 v235, 0xbfb8aa3b, v100
	v_mul_f32_e32 v236, 0xbfb8aa3b, v101
	v_mul_f32_e32 v237, 0xbfb8aa3b, v102
	v_mul_f32_e32 v238, 0xbfb8aa3b, v103
	v_mul_f32_e32 v239, 0xbfb8aa3b, v96
	v_mul_f32_e32 v240, 0xbfb8aa3b, v97
	v_mul_f32_e32 v241, 0xbfb8aa3b, v98
	v_mul_f32_e32 v242, 0xbfb8aa3b, v99
	v_exp_f32_e32 v235, v235
	v_exp_f32_e32 v236, v236
	v_exp_f32_e32 v237, v237
	v_exp_f32_e32 v238, v238
	v_exp_f32_e32 v239, v239
	v_exp_f32_e32 v240, v240
	v_exp_f32_e32 v241, v241
	v_exp_f32_e32 v242, v242
	v_add_f32_e32 v235, 1.0, v235
	v_add_f32_e32 v236, 1.0, v236
	v_add_f32_e32 v237, 1.0, v237
	v_add_f32_e32 v238, 1.0, v238
	v_add_f32_e32 v239, 1.0, v239
	v_add_f32_e32 v240, 1.0, v240
	v_add_f32_e32 v241, 1.0, v241
	v_add_f32_e32 v242, 1.0, v242
	v_rcp_f32_e32 v235, v235
	v_rcp_f32_e32 v236, v236
	v_rcp_f32_e32 v237, v237
	v_rcp_f32_e32 v238, v238
	v_rcp_f32_e32 v239, v239
	v_rcp_f32_e32 v240, v240
	v_rcp_f32_e32 v241, v241
	v_rcp_f32_e32 v242, v242
	s_waitcnt vmcnt(19)
	v_lshlrev_b32_e32 v160, 16, v210
	v_lshlrev_b32_e32 v161, 16, v214
	v_mul_f32_e32 v235, v235, v160
	v_mul_f32_e32 v235, v235, v161
	v_and_b32_e32 v160, 0xffff0000, v210
	v_and_b32_e32 v161, 0xffff0000, v214
	v_mul_f32_e32 v236, v236, v160
	v_mul_f32_e32 v236, v236, v161
	v_cvt_pk_bf16_f32 v248, v235, v236
	v_lshlrev_b32_e32 v160, 16, v211
	v_lshlrev_b32_e32 v161, 16, v215
	v_mul_f32_e32 v237, v237, v160
	v_mul_f32_e32 v237, v237, v161
	v_and_b32_e32 v160, 0xffff0000, v211
	v_and_b32_e32 v161, 0xffff0000, v215
	v_mul_f32_e32 v238, v238, v160
	v_mul_f32_e32 v238, v238, v161
	v_cvt_pk_bf16_f32 v249, v237, v238
	v_lshlrev_b32_e32 v160, 16, v212
	v_lshlrev_b32_e32 v161, 16, v216
	v_mul_f32_e32 v239, v239, v160
	v_mul_f32_e32 v239, v239, v161
	v_and_b32_e32 v160, 0xffff0000, v212
	v_and_b32_e32 v161, 0xffff0000, v216
	v_mul_f32_e32 v240, v240, v160
	v_mul_f32_e32 v240, v240, v161
	v_cvt_pk_bf16_f32 v250, v239, v240
	v_lshlrev_b32_e32 v160, 16, v213
	v_lshlrev_b32_e32 v161, 16, v217
	v_mul_f32_e32 v241, v241, v160
	v_mul_f32_e32 v241, v241, v161
	v_and_b32_e32 v160, 0xffff0000, v213
	v_and_b32_e32 v161, 0xffff0000, v217
	v_mul_f32_e32 v242, v242, v160
	v_mul_f32_e32 v242, v242, v161
	v_cvt_pk_bf16_f32 v251, v241, v242
	global_store_dwordx4 v255, v[248:251], s[44:45] offset:256
	s_add_u32 s44, s44, 0x10000
	s_addc_u32 s45, s45, 0
	global_load_dwordx4 v[100:103], v254, s[66:67] offset:256
	global_load_dwordx4 v[96:99], v254, s[68:69] offset:256
	s_add_u32 s66, s66, 0x8000
	s_addc_u32 s67, s67, 0
	s_add_u32 s68, s68, 0x8000
	s_addc_u32 s69, s69, 0
	v_add_f32_e32 v92, v92, v40
	v_add_f32_e32 v93, v93, v41
	v_add_f32_e32 v94, v94, v42
	v_add_f32_e32 v95, v95, v43
	v_add_f32_e32 v88, v88, v44
	v_add_f32_e32 v89, v89, v45
	v_add_f32_e32 v90, v90, v46
	v_add_f32_e32 v91, v91, v47
	v_mul_f32_e32 v235, 0xbfb8aa3b, v92
	v_mul_f32_e32 v236, 0xbfb8aa3b, v93
	v_mul_f32_e32 v237, 0xbfb8aa3b, v94
	v_mul_f32_e32 v238, 0xbfb8aa3b, v95
	v_mul_f32_e32 v239, 0xbfb8aa3b, v88
	v_mul_f32_e32 v240, 0xbfb8aa3b, v89
	v_mul_f32_e32 v241, 0xbfb8aa3b, v90
	v_mul_f32_e32 v242, 0xbfb8aa3b, v91
	v_exp_f32_e32 v235, v235
	v_exp_f32_e32 v236, v236
	v_exp_f32_e32 v237, v237
	v_exp_f32_e32 v238, v238
	v_exp_f32_e32 v239, v239
	v_exp_f32_e32 v240, v240
	v_exp_f32_e32 v241, v241
	v_exp_f32_e32 v242, v242
	v_add_f32_e32 v235, 1.0, v235
	v_add_f32_e32 v236, 1.0, v236
	v_add_f32_e32 v237, 1.0, v237
	v_add_f32_e32 v238, 1.0, v238
	v_add_f32_e32 v239, 1.0, v239
	v_add_f32_e32 v240, 1.0, v240
	v_add_f32_e32 v241, 1.0, v241
	v_add_f32_e32 v242, 1.0, v242
	v_rcp_f32_e32 v235, v235
	v_rcp_f32_e32 v236, v236
	v_rcp_f32_e32 v237, v237
	v_rcp_f32_e32 v238, v238
	v_rcp_f32_e32 v239, v239
	v_rcp_f32_e32 v240, v240
	v_rcp_f32_e32 v241, v241
	v_rcp_f32_e32 v242, v242
	s_waitcnt vmcnt(20)
	v_lshlrev_b32_e32 v160, 16, v218
	v_lshlrev_b32_e32 v161, 16, v222
	v_mul_f32_e32 v235, v235, v160
	v_mul_f32_e32 v235, v235, v161
	v_and_b32_e32 v160, 0xffff0000, v218
	v_and_b32_e32 v161, 0xffff0000, v222
	v_mul_f32_e32 v236, v236, v160
	v_mul_f32_e32 v236, v236, v161
	v_cvt_pk_bf16_f32 v244, v235, v236
	v_lshlrev_b32_e32 v160, 16, v219
	v_lshlrev_b32_e32 v161, 16, v223
	v_mul_f32_e32 v237, v237, v160
	v_mul_f32_e32 v237, v237, v161
	v_and_b32_e32 v160, 0xffff0000, v219
	v_and_b32_e32 v161, 0xffff0000, v223
	v_mul_f32_e32 v238, v238, v160
	v_mul_f32_e32 v238, v238, v161
	v_cvt_pk_bf16_f32 v245, v237, v238
	v_lshlrev_b32_e32 v160, 16, v220
	v_lshlrev_b32_e32 v161, 16, v224
	v_mul_f32_e32 v239, v239, v160
	v_mul_f32_e32 v239, v239, v161
	v_and_b32_e32 v160, 0xffff0000, v220
	v_and_b32_e32 v161, 0xffff0000, v224
	v_mul_f32_e32 v240, v240, v160
	v_mul_f32_e32 v240, v240, v161
	v_cvt_pk_bf16_f32 v246, v239, v240
	v_lshlrev_b32_e32 v160, 16, v221
	v_lshlrev_b32_e32 v161, 16, v225
	v_mul_f32_e32 v241, v241, v160
	v_mul_f32_e32 v241, v241, v161
	v_and_b32_e32 v160, 0xffff0000, v221
	v_and_b32_e32 v161, 0xffff0000, v225
	v_mul_f32_e32 v242, v242, v160
	v_mul_f32_e32 v242, v242, v161
	v_cvt_pk_bf16_f32 v247, v241, v242
	global_store_dwordx4 v255, v[244:247], s[44:45]
	global_load_dwordx4 v[92:95], v254, s[66:67]
	global_load_dwordx4 v[88:91], v254, s[68:69]
	v_add_f32_e32 v84, v84, v64
	v_add_f32_e32 v85, v85, v65
	v_add_f32_e32 v86, v86, v66
	v_add_f32_e32 v87, v87, v67
	v_add_f32_e32 v80, v80, v68
	v_add_f32_e32 v81, v81, v69
	v_add_f32_e32 v82, v82, v70
	v_add_f32_e32 v83, v83, v71
	v_mul_f32_e32 v235, 0xbfb8aa3b, v84
	v_mul_f32_e32 v236, 0xbfb8aa3b, v85
	v_mul_f32_e32 v237, 0xbfb8aa3b, v86
	v_mul_f32_e32 v238, 0xbfb8aa3b, v87
	v_mul_f32_e32 v239, 0xbfb8aa3b, v80
	v_mul_f32_e32 v240, 0xbfb8aa3b, v81
	v_mul_f32_e32 v241, 0xbfb8aa3b, v82
	v_mul_f32_e32 v242, 0xbfb8aa3b, v83
	v_exp_f32_e32 v235, v235
	v_exp_f32_e32 v236, v236
	v_exp_f32_e32 v237, v237
	v_exp_f32_e32 v238, v238
	v_exp_f32_e32 v239, v239
	v_exp_f32_e32 v240, v240
	v_exp_f32_e32 v241, v241
	v_exp_f32_e32 v242, v242
	v_add_f32_e32 v235, 1.0, v235
	v_add_f32_e32 v236, 1.0, v236
	v_add_f32_e32 v237, 1.0, v237
	v_add_f32_e32 v238, 1.0, v238
	v_add_f32_e32 v239, 1.0, v239
	v_add_f32_e32 v240, 1.0, v240
	v_add_f32_e32 v241, 1.0, v241
	v_add_f32_e32 v242, 1.0, v242
	v_rcp_f32_e32 v235, v235
	v_rcp_f32_e32 v236, v236
	v_rcp_f32_e32 v237, v237
	v_rcp_f32_e32 v238, v238
	v_rcp_f32_e32 v239, v239
	v_rcp_f32_e32 v240, v240
	v_rcp_f32_e32 v241, v241
	v_rcp_f32_e32 v242, v242
	s_waitcnt vmcnt(21)
	v_lshlrev_b32_e32 v160, 16, v226
	v_lshlrev_b32_e32 v161, 16, v230
	v_mul_f32_e32 v235, v235, v160
	v_mul_f32_e32 v235, v235, v161
	v_and_b32_e32 v160, 0xffff0000, v226
	v_and_b32_e32 v161, 0xffff0000, v230
	v_mul_f32_e32 v236, v236, v160
	v_mul_f32_e32 v236, v236, v161
	v_cvt_pk_bf16_f32 v248, v235, v236
	v_lshlrev_b32_e32 v160, 16, v227
	v_lshlrev_b32_e32 v161, 16, v231
	v_mul_f32_e32 v237, v237, v160
	v_mul_f32_e32 v237, v237, v161
	v_and_b32_e32 v160, 0xffff0000, v227
	v_and_b32_e32 v161, 0xffff0000, v231
	v_mul_f32_e32 v238, v238, v160
	v_mul_f32_e32 v238, v238, v161
	v_cvt_pk_bf16_f32 v249, v237, v238
	v_lshlrev_b32_e32 v160, 16, v228
	v_lshlrev_b32_e32 v161, 16, v232
	v_mul_f32_e32 v239, v239, v160
	v_mul_f32_e32 v239, v239, v161
	v_and_b32_e32 v160, 0xffff0000, v228
	v_and_b32_e32 v161, 0xffff0000, v232
	v_mul_f32_e32 v240, v240, v160
	v_mul_f32_e32 v240, v240, v161
	v_cvt_pk_bf16_f32 v250, v239, v240
	v_lshlrev_b32_e32 v160, 16, v229
	v_lshlrev_b32_e32 v161, 16, v233
	v_mul_f32_e32 v241, v241, v160
	v_mul_f32_e32 v241, v241, v161
	v_and_b32_e32 v160, 0xffff0000, v229
	v_and_b32_e32 v161, 0xffff0000, v233
	v_mul_f32_e32 v242, v242, v160
	v_mul_f32_e32 v242, v242, v161
	v_cvt_pk_bf16_f32 v251, v241, v242
	global_store_dwordx4 v255, v[248:251], s[44:45] offset:256
	global_load_dwordx4 v[84:87], v254, s[66:67] offset:256
	global_load_dwordx4 v[80:83], v254, s[68:69] offset:256
	v_add_f32_e32 v76, v76, v40
	v_add_f32_e32 v77, v77, v41
	v_add_f32_e32 v78, v78, v42
	v_add_f32_e32 v79, v79, v43
	v_add_f32_e32 v72, v72, v44
	v_add_f32_e32 v73, v73, v45
	v_add_f32_e32 v74, v74, v46
	v_add_f32_e32 v75, v75, v47
	v_mul_f32_e32 v235, 0xbfb8aa3b, v76
	v_mul_f32_e32 v236, 0xbfb8aa3b, v77
	v_mul_f32_e32 v237, 0xbfb8aa3b, v78
	v_mul_f32_e32 v238, 0xbfb8aa3b, v79
	v_mul_f32_e32 v239, 0xbfb8aa3b, v72
	v_mul_f32_e32 v240, 0xbfb8aa3b, v73
	v_mul_f32_e32 v241, 0xbfb8aa3b, v74
	v_mul_f32_e32 v242, 0xbfb8aa3b, v75
	v_exp_f32_e32 v235, v235
	v_exp_f32_e32 v236, v236
	v_exp_f32_e32 v237, v237
	v_exp_f32_e32 v238, v238
	v_exp_f32_e32 v239, v239
	v_exp_f32_e32 v240, v240
	v_exp_f32_e32 v241, v241
	v_exp_f32_e32 v242, v242
	v_add_f32_e32 v235, 1.0, v235
	v_add_f32_e32 v236, 1.0, v236
	v_add_f32_e32 v237, 1.0, v237
	v_add_f32_e32 v238, 1.0, v238
	v_add_f32_e32 v239, 1.0, v239
	v_add_f32_e32 v240, 1.0, v240
	v_add_f32_e32 v241, 1.0, v241
	v_add_f32_e32 v242, 1.0, v242
	v_rcp_f32_e32 v235, v235
	v_rcp_f32_e32 v236, v236
	v_rcp_f32_e32 v237, v237
	v_rcp_f32_e32 v238, v238
	v_rcp_f32_e32 v239, v239
	v_rcp_f32_e32 v240, v240
	v_rcp_f32_e32 v241, v241
	v_rcp_f32_e32 v242, v242
	s_waitcnt vmcnt(21)
	v_lshlrev_b32_e32 v160, 16, v140
	v_lshlrev_b32_e32 v161, 16, v136
	v_mul_f32_e32 v235, v235, v160
	v_mul_f32_e32 v235, v235, v161
	v_and_b32_e32 v160, 0xffff0000, v140
	v_and_b32_e32 v161, 0xffff0000, v136
	v_mul_f32_e32 v236, v236, v160
	v_mul_f32_e32 v236, v236, v161
	v_cvt_pk_bf16_f32 v244, v235, v236
	v_lshlrev_b32_e32 v160, 16, v141
	v_lshlrev_b32_e32 v161, 16, v137
	v_mul_f32_e32 v237, v237, v160
	v_mul_f32_e32 v237, v237, v161
	v_and_b32_e32 v160, 0xffff0000, v141
	v_and_b32_e32 v161, 0xffff0000, v137
	v_mul_f32_e32 v238, v238, v160
	v_mul_f32_e32 v238, v238, v161
	v_cvt_pk_bf16_f32 v245, v237, v238
	v_lshlrev_b32_e32 v160, 16, v142
	v_lshlrev_b32_e32 v161, 16, v138
	v_mul_f32_e32 v239, v239, v160
	v_mul_f32_e32 v239, v239, v161
	v_and_b32_e32 v160, 0xffff0000, v142
	v_and_b32_e32 v161, 0xffff0000, v138
	v_mul_f32_e32 v240, v240, v160
	v_mul_f32_e32 v240, v240, v161
	v_cvt_pk_bf16_f32 v246, v239, v240
	v_lshlrev_b32_e32 v160, 16, v143
	v_lshlrev_b32_e32 v161, 16, v139
	v_mul_f32_e32 v241, v241, v160
	v_mul_f32_e32 v241, v241, v161
	v_and_b32_e32 v160, 0xffff0000, v143
	v_and_b32_e32 v161, 0xffff0000, v139
	v_mul_f32_e32 v242, v242, v160
	v_mul_f32_e32 v242, v242, v161
	v_cvt_pk_bf16_f32 v247, v241, v242
	global_store_dwordx4 v255, v[244:247], s[70:71]
	v_add_f32_e32 v60, v60, v64
	v_add_f32_e32 v61, v61, v65
	v_add_f32_e32 v62, v62, v66
	v_add_f32_e32 v63, v63, v67
	v_add_f32_e32 v56, v56, v68
	v_add_f32_e32 v57, v57, v69
	v_add_f32_e32 v58, v58, v70
	v_add_f32_e32 v59, v59, v71
	v_mul_f32_e32 v235, 0xbfb8aa3b, v60
	v_mul_f32_e32 v236, 0xbfb8aa3b, v61
	v_mul_f32_e32 v237, 0xbfb8aa3b, v62
	v_mul_f32_e32 v238, 0xbfb8aa3b, v63
	v_mul_f32_e32 v239, 0xbfb8aa3b, v56
	v_mul_f32_e32 v240, 0xbfb8aa3b, v57
	v_mul_f32_e32 v241, 0xbfb8aa3b, v58
	v_mul_f32_e32 v242, 0xbfb8aa3b, v59
	v_exp_f32_e32 v235, v235
	v_exp_f32_e32 v236, v236
	v_exp_f32_e32 v237, v237
	v_exp_f32_e32 v238, v238
	v_exp_f32_e32 v239, v239
	v_exp_f32_e32 v240, v240
	v_exp_f32_e32 v241, v241
	v_exp_f32_e32 v242, v242
	v_add_f32_e32 v235, 1.0, v235
	v_add_f32_e32 v236, 1.0, v236
	v_add_f32_e32 v237, 1.0, v237
	v_add_f32_e32 v238, 1.0, v238
	v_add_f32_e32 v239, 1.0, v239
	v_add_f32_e32 v240, 1.0, v240
	v_add_f32_e32 v241, 1.0, v241
	v_add_f32_e32 v242, 1.0, v242
	v_rcp_f32_e32 v235, v235
	v_rcp_f32_e32 v236, v236
	v_rcp_f32_e32 v237, v237
	v_rcp_f32_e32 v238, v238
	v_rcp_f32_e32 v239, v239
	v_rcp_f32_e32 v240, v240
	v_rcp_f32_e32 v241, v241
	v_rcp_f32_e32 v242, v242
	s_waitcnt vmcnt(19)
	v_lshlrev_b32_e32 v160, 16, v132
	v_lshlrev_b32_e32 v161, 16, v128
	v_mul_f32_e32 v235, v235, v160
	v_mul_f32_e32 v235, v235, v161
	v_and_b32_e32 v160, 0xffff0000, v132
	v_and_b32_e32 v161, 0xffff0000, v128
	v_mul_f32_e32 v236, v236, v160
	v_mul_f32_e32 v236, v236, v161
	v_cvt_pk_bf16_f32 v248, v235, v236
	v_lshlrev_b32_e32 v160, 16, v133
	v_lshlrev_b32_e32 v161, 16, v129
	v_mul_f32_e32 v237, v237, v160
	v_mul_f32_e32 v237, v237, v161
	v_and_b32_e32 v160, 0xffff0000, v133
	v_and_b32_e32 v161, 0xffff0000, v129
	v_mul_f32_e32 v238, v238, v160
	v_mul_f32_e32 v238, v238, v161
	v_cvt_pk_bf16_f32 v249, v237, v238
	v_lshlrev_b32_e32 v160, 16, v134
	v_lshlrev_b32_e32 v161, 16, v130
	v_mul_f32_e32 v239, v239, v160
	v_mul_f32_e32 v239, v239, v161
	v_and_b32_e32 v160, 0xffff0000, v134
	v_and_b32_e32 v161, 0xffff0000, v130
	v_mul_f32_e32 v240, v240, v160
	v_mul_f32_e32 v240, v240, v161
	v_cvt_pk_bf16_f32 v250, v239, v240
	v_lshlrev_b32_e32 v160, 16, v135
	v_lshlrev_b32_e32 v161, 16, v131
	v_mul_f32_e32 v241, v241, v160
	v_mul_f32_e32 v241, v241, v161
	v_and_b32_e32 v160, 0xffff0000, v135
	v_and_b32_e32 v161, 0xffff0000, v131
	v_mul_f32_e32 v242, v242, v160
	v_mul_f32_e32 v242, v242, v161
	v_cvt_pk_bf16_f32 v251, v241, v242
	global_store_dwordx4 v255, v[248:251], s[70:71] offset:256
	s_add_u32 s70, s70, 0x10000
	s_addc_u32 s71, s71, 0
	v_add_f32_e32 v52, v52, v40
	v_add_f32_e32 v53, v53, v41
	v_add_f32_e32 v54, v54, v42
	v_add_f32_e32 v55, v55, v43
	v_add_f32_e32 v48, v48, v44
	v_add_f32_e32 v49, v49, v45
	v_add_f32_e32 v50, v50, v46
	v_add_f32_e32 v51, v51, v47
	v_mul_f32_e32 v235, 0xbfb8aa3b, v52
	v_mul_f32_e32 v236, 0xbfb8aa3b, v53
	v_mul_f32_e32 v237, 0xbfb8aa3b, v54
	v_mul_f32_e32 v238, 0xbfb8aa3b, v55
	v_mul_f32_e32 v239, 0xbfb8aa3b, v48
	v_mul_f32_e32 v240, 0xbfb8aa3b, v49
	v_mul_f32_e32 v241, 0xbfb8aa3b, v50
	v_mul_f32_e32 v242, 0xbfb8aa3b, v51
	v_exp_f32_e32 v235, v235
	v_exp_f32_e32 v236, v236
	v_exp_f32_e32 v237, v237
	v_exp_f32_e32 v238, v238
	v_exp_f32_e32 v239, v239
	v_exp_f32_e32 v240, v240
	v_exp_f32_e32 v241, v241
	v_exp_f32_e32 v242, v242
	v_add_f32_e32 v235, 1.0, v235
	v_add_f32_e32 v236, 1.0, v236
	v_add_f32_e32 v237, 1.0, v237
	v_add_f32_e32 v238, 1.0, v238
	v_add_f32_e32 v239, 1.0, v239
	v_add_f32_e32 v240, 1.0, v240
	v_add_f32_e32 v241, 1.0, v241
	v_add_f32_e32 v242, 1.0, v242
	v_rcp_f32_e32 v235, v235
	v_rcp_f32_e32 v236, v236
	v_rcp_f32_e32 v237, v237
	v_rcp_f32_e32 v238, v238
	v_rcp_f32_e32 v239, v239
	v_rcp_f32_e32 v240, v240
	v_rcp_f32_e32 v241, v241
	v_rcp_f32_e32 v242, v242
	s_waitcnt vmcnt(17)
	v_lshlrev_b32_e32 v160, 16, v124
	v_lshlrev_b32_e32 v161, 16, v120
	v_mul_f32_e32 v235, v235, v160
	v_mul_f32_e32 v235, v235, v161
	v_and_b32_e32 v160, 0xffff0000, v124
	v_and_b32_e32 v161, 0xffff0000, v120
	v_mul_f32_e32 v236, v236, v160
	v_mul_f32_e32 v236, v236, v161
	v_cvt_pk_bf16_f32 v244, v235, v236
	v_lshlrev_b32_e32 v160, 16, v125
	v_lshlrev_b32_e32 v161, 16, v121
	v_mul_f32_e32 v237, v237, v160
	v_mul_f32_e32 v237, v237, v161
	v_and_b32_e32 v160, 0xffff0000, v125
	v_and_b32_e32 v161, 0xffff0000, v121
	v_mul_f32_e32 v238, v238, v160
	v_mul_f32_e32 v238, v238, v161
	v_cvt_pk_bf16_f32 v245, v237, v238
	v_lshlrev_b32_e32 v160, 16, v126
	v_lshlrev_b32_e32 v161, 16, v122
	v_mul_f32_e32 v239, v239, v160
	v_mul_f32_e32 v239, v239, v161
	v_and_b32_e32 v160, 0xffff0000, v126
	v_and_b32_e32 v161, 0xffff0000, v122
	v_mul_f32_e32 v240, v240, v160
	v_mul_f32_e32 v240, v240, v161
	v_cvt_pk_bf16_f32 v246, v239, v240
	v_lshlrev_b32_e32 v160, 16, v127
	v_lshlrev_b32_e32 v161, 16, v123
	v_mul_f32_e32 v241, v241, v160
	v_mul_f32_e32 v241, v241, v161
	v_and_b32_e32 v160, 0xffff0000, v127
	v_and_b32_e32 v161, 0xffff0000, v123
	v_mul_f32_e32 v242, v242, v160
	v_mul_f32_e32 v242, v242, v161
	v_cvt_pk_bf16_f32 v247, v241, v242
	global_store_dwordx4 v255, v[244:247], s[70:71]
	v_add_f32_e32 v36, v36, v64
	v_add_f32_e32 v37, v37, v65
	v_add_f32_e32 v38, v38, v66
	v_add_f32_e32 v39, v39, v67
	v_add_f32_e32 v32, v32, v68
	v_add_f32_e32 v33, v33, v69
	v_add_f32_e32 v34, v34, v70
	v_add_f32_e32 v35, v35, v71
	v_mul_f32_e32 v235, 0xbfb8aa3b, v36
	v_mul_f32_e32 v236, 0xbfb8aa3b, v37
	v_mul_f32_e32 v237, 0xbfb8aa3b, v38
	v_mul_f32_e32 v238, 0xbfb8aa3b, v39
	v_mul_f32_e32 v239, 0xbfb8aa3b, v32
	v_mul_f32_e32 v240, 0xbfb8aa3b, v33
	v_mul_f32_e32 v241, 0xbfb8aa3b, v34
	v_mul_f32_e32 v242, 0xbfb8aa3b, v35
	v_exp_f32_e32 v235, v235
	v_exp_f32_e32 v236, v236
	v_exp_f32_e32 v237, v237
	v_exp_f32_e32 v238, v238
	v_exp_f32_e32 v239, v239
	v_exp_f32_e32 v240, v240
	v_exp_f32_e32 v241, v241
	v_exp_f32_e32 v242, v242
	v_add_f32_e32 v235, 1.0, v235
	v_add_f32_e32 v236, 1.0, v236
	v_add_f32_e32 v237, 1.0, v237
	v_add_f32_e32 v238, 1.0, v238
	v_add_f32_e32 v239, 1.0, v239
	v_add_f32_e32 v240, 1.0, v240
	v_add_f32_e32 v241, 1.0, v241
	v_add_f32_e32 v242, 1.0, v242
	v_rcp_f32_e32 v235, v235
	v_rcp_f32_e32 v236, v236
	v_rcp_f32_e32 v237, v237
	v_rcp_f32_e32 v238, v238
	v_rcp_f32_e32 v239, v239
	v_rcp_f32_e32 v240, v240
	v_rcp_f32_e32 v241, v241
	v_rcp_f32_e32 v242, v242
	s_waitcnt vmcnt(15)
	v_lshlrev_b32_e32 v160, 16, v116
	v_lshlrev_b32_e32 v161, 16, v112
	v_mul_f32_e32 v235, v235, v160
	v_mul_f32_e32 v235, v235, v161
	v_and_b32_e32 v160, 0xffff0000, v116
	v_and_b32_e32 v161, 0xffff0000, v112
	v_mul_f32_e32 v236, v236, v160
	v_mul_f32_e32 v236, v236, v161
	v_cvt_pk_bf16_f32 v248, v235, v236
	v_lshlrev_b32_e32 v160, 16, v117
	v_lshlrev_b32_e32 v161, 16, v113
	v_mul_f32_e32 v237, v237, v160
	v_mul_f32_e32 v237, v237, v161
	v_and_b32_e32 v160, 0xffff0000, v117
	v_and_b32_e32 v161, 0xffff0000, v113
	v_mul_f32_e32 v238, v238, v160
	v_mul_f32_e32 v238, v238, v161
	v_cvt_pk_bf16_f32 v249, v237, v238
	v_lshlrev_b32_e32 v160, 16, v118
	v_lshlrev_b32_e32 v161, 16, v114
	v_mul_f32_e32 v239, v239, v160
	v_mul_f32_e32 v239, v239, v161
	v_and_b32_e32 v160, 0xffff0000, v118
	v_and_b32_e32 v161, 0xffff0000, v114
	v_mul_f32_e32 v240, v240, v160
	v_mul_f32_e32 v240, v240, v161
	v_cvt_pk_bf16_f32 v250, v239, v240
	v_lshlrev_b32_e32 v160, 16, v119
	v_lshlrev_b32_e32 v161, 16, v115
	v_mul_f32_e32 v241, v241, v160
	v_mul_f32_e32 v241, v241, v161
	v_and_b32_e32 v160, 0xffff0000, v119
	v_and_b32_e32 v161, 0xffff0000, v115
	v_mul_f32_e32 v242, v242, v160
	v_mul_f32_e32 v242, v242, v161
	v_cvt_pk_bf16_f32 v251, v241, v242
	global_store_dwordx4 v255, v[248:251], s[70:71] offset:256
	s_add_u32 s70, s70, 0x10000
	s_addc_u32 s71, s71, 0
	v_add_f32_e32 v28, v28, v40
	v_add_f32_e32 v29, v29, v41
	v_add_f32_e32 v30, v30, v42
	v_add_f32_e32 v31, v31, v43
	v_add_f32_e32 v24, v24, v44
	v_add_f32_e32 v25, v25, v45
	v_add_f32_e32 v26, v26, v46
	v_add_f32_e32 v27, v27, v47
	v_mul_f32_e32 v235, 0xbfb8aa3b, v28
	v_mul_f32_e32 v236, 0xbfb8aa3b, v29
	v_mul_f32_e32 v237, 0xbfb8aa3b, v30
	v_mul_f32_e32 v238, 0xbfb8aa3b, v31
	v_mul_f32_e32 v239, 0xbfb8aa3b, v24
	v_mul_f32_e32 v240, 0xbfb8aa3b, v25
	v_mul_f32_e32 v241, 0xbfb8aa3b, v26
	v_mul_f32_e32 v242, 0xbfb8aa3b, v27
	v_exp_f32_e32 v235, v235
	v_exp_f32_e32 v236, v236
	v_exp_f32_e32 v237, v237
	v_exp_f32_e32 v238, v238
	v_exp_f32_e32 v239, v239
	v_exp_f32_e32 v240, v240
	v_exp_f32_e32 v241, v241
	v_exp_f32_e32 v242, v242
	v_add_f32_e32 v235, 1.0, v235
	v_add_f32_e32 v236, 1.0, v236
	v_add_f32_e32 v237, 1.0, v237
	v_add_f32_e32 v238, 1.0, v238
	v_add_f32_e32 v239, 1.0, v239
	v_add_f32_e32 v240, 1.0, v240
	v_add_f32_e32 v241, 1.0, v241
	v_add_f32_e32 v242, 1.0, v242
	v_rcp_f32_e32 v235, v235
	v_rcp_f32_e32 v236, v236
	v_rcp_f32_e32 v237, v237
	v_rcp_f32_e32 v238, v238
	v_rcp_f32_e32 v239, v239
	v_rcp_f32_e32 v240, v240
	v_rcp_f32_e32 v241, v241
	v_rcp_f32_e32 v242, v242
	s_waitcnt vmcnt(13)
	v_lshlrev_b32_e32 v160, 16, v108
	v_lshlrev_b32_e32 v161, 16, v104
	v_mul_f32_e32 v235, v235, v160
	v_mul_f32_e32 v235, v235, v161
	v_and_b32_e32 v160, 0xffff0000, v108
	v_and_b32_e32 v161, 0xffff0000, v104
	v_mul_f32_e32 v236, v236, v160
	v_mul_f32_e32 v236, v236, v161
	v_cvt_pk_bf16_f32 v244, v235, v236
	v_lshlrev_b32_e32 v160, 16, v109
	v_lshlrev_b32_e32 v161, 16, v105
	v_mul_f32_e32 v237, v237, v160
	v_mul_f32_e32 v237, v237, v161
	v_and_b32_e32 v160, 0xffff0000, v109
	v_and_b32_e32 v161, 0xffff0000, v105
	v_mul_f32_e32 v238, v238, v160
	v_mul_f32_e32 v238, v238, v161
	v_cvt_pk_bf16_f32 v245, v237, v238
	v_lshlrev_b32_e32 v160, 16, v110
	v_lshlrev_b32_e32 v161, 16, v106
	v_mul_f32_e32 v239, v239, v160
	v_mul_f32_e32 v239, v239, v161
	v_and_b32_e32 v160, 0xffff0000, v110
	v_and_b32_e32 v161, 0xffff0000, v106
	v_mul_f32_e32 v240, v240, v160
	v_mul_f32_e32 v240, v240, v161
	v_cvt_pk_bf16_f32 v246, v239, v240
	v_lshlrev_b32_e32 v160, 16, v111
	v_lshlrev_b32_e32 v161, 16, v107
	v_mul_f32_e32 v241, v241, v160
	v_mul_f32_e32 v241, v241, v161
	v_and_b32_e32 v160, 0xffff0000, v111
	v_and_b32_e32 v161, 0xffff0000, v107
	v_mul_f32_e32 v242, v242, v160
	v_mul_f32_e32 v242, v242, v161
	v_cvt_pk_bf16_f32 v247, v241, v242
	global_store_dwordx4 v255, v[244:247], s[70:71]
	v_add_f32_e32 v20, v20, v64
	v_add_f32_e32 v21, v21, v65
	v_add_f32_e32 v22, v22, v66
	v_add_f32_e32 v23, v23, v67
	v_add_f32_e32 v16, v16, v68
	v_add_f32_e32 v17, v17, v69
	v_add_f32_e32 v18, v18, v70
	v_add_f32_e32 v19, v19, v71
	v_mul_f32_e32 v235, 0xbfb8aa3b, v20
	v_mul_f32_e32 v236, 0xbfb8aa3b, v21
	v_mul_f32_e32 v237, 0xbfb8aa3b, v22
	v_mul_f32_e32 v238, 0xbfb8aa3b, v23
	v_mul_f32_e32 v239, 0xbfb8aa3b, v16
	v_mul_f32_e32 v240, 0xbfb8aa3b, v17
	v_mul_f32_e32 v241, 0xbfb8aa3b, v18
	v_mul_f32_e32 v242, 0xbfb8aa3b, v19
	v_exp_f32_e32 v235, v235
	v_exp_f32_e32 v236, v236
	v_exp_f32_e32 v237, v237
	v_exp_f32_e32 v238, v238
	v_exp_f32_e32 v239, v239
	v_exp_f32_e32 v240, v240
	v_exp_f32_e32 v241, v241
	v_exp_f32_e32 v242, v242
	v_add_f32_e32 v235, 1.0, v235
	v_add_f32_e32 v236, 1.0, v236
	v_add_f32_e32 v237, 1.0, v237
	v_add_f32_e32 v238, 1.0, v238
	v_add_f32_e32 v239, 1.0, v239
	v_add_f32_e32 v240, 1.0, v240
	v_add_f32_e32 v241, 1.0, v241
	v_add_f32_e32 v242, 1.0, v242
	v_rcp_f32_e32 v235, v235
	v_rcp_f32_e32 v236, v236
	v_rcp_f32_e32 v237, v237
	v_rcp_f32_e32 v238, v238
	v_rcp_f32_e32 v239, v239
	v_rcp_f32_e32 v240, v240
	v_rcp_f32_e32 v241, v241
	v_rcp_f32_e32 v242, v242
	s_waitcnt vmcnt(11)
	v_lshlrev_b32_e32 v160, 16, v100
	v_lshlrev_b32_e32 v161, 16, v96
	v_mul_f32_e32 v235, v235, v160
	v_mul_f32_e32 v235, v235, v161
	v_and_b32_e32 v160, 0xffff0000, v100
	v_and_b32_e32 v161, 0xffff0000, v96
	v_mul_f32_e32 v236, v236, v160
	v_mul_f32_e32 v236, v236, v161
	v_cvt_pk_bf16_f32 v248, v235, v236
	v_lshlrev_b32_e32 v160, 16, v101
	v_lshlrev_b32_e32 v161, 16, v97
	v_mul_f32_e32 v237, v237, v160
	v_mul_f32_e32 v237, v237, v161
	v_and_b32_e32 v160, 0xffff0000, v101
	v_and_b32_e32 v161, 0xffff0000, v97
	v_mul_f32_e32 v238, v238, v160
	v_mul_f32_e32 v238, v238, v161
	v_cvt_pk_bf16_f32 v249, v237, v238
	v_lshlrev_b32_e32 v160, 16, v102
	v_lshlrev_b32_e32 v161, 16, v98
	v_mul_f32_e32 v239, v239, v160
	v_mul_f32_e32 v239, v239, v161
	v_and_b32_e32 v160, 0xffff0000, v102
	v_and_b32_e32 v161, 0xffff0000, v98
	v_mul_f32_e32 v240, v240, v160
	v_mul_f32_e32 v240, v240, v161
	v_cvt_pk_bf16_f32 v250, v239, v240
	v_lshlrev_b32_e32 v160, 16, v103
	v_lshlrev_b32_e32 v161, 16, v99
	v_mul_f32_e32 v241, v241, v160
	v_mul_f32_e32 v241, v241, v161
	v_and_b32_e32 v160, 0xffff0000, v103
	v_and_b32_e32 v161, 0xffff0000, v99
	v_mul_f32_e32 v242, v242, v160
	v_mul_f32_e32 v242, v242, v161
	v_cvt_pk_bf16_f32 v251, v241, v242
	global_store_dwordx4 v255, v[248:251], s[70:71] offset:256
	s_add_u32 s70, s70, 0x10000
	s_addc_u32 s71, s71, 0
	v_add_f32_e32 v12, v12, v40
	v_add_f32_e32 v13, v13, v41
	v_add_f32_e32 v14, v14, v42
	v_add_f32_e32 v15, v15, v43
	v_add_f32_e32 v8, v8, v44
	v_add_f32_e32 v9, v9, v45
	v_add_f32_e32 v10, v10, v46
	v_add_f32_e32 v11, v11, v47
	v_mul_f32_e32 v235, 0xbfb8aa3b, v12
	v_mul_f32_e32 v236, 0xbfb8aa3b, v13
	v_mul_f32_e32 v237, 0xbfb8aa3b, v14
	v_mul_f32_e32 v238, 0xbfb8aa3b, v15
	v_mul_f32_e32 v239, 0xbfb8aa3b, v8
	v_mul_f32_e32 v240, 0xbfb8aa3b, v9
	v_mul_f32_e32 v241, 0xbfb8aa3b, v10
	v_mul_f32_e32 v242, 0xbfb8aa3b, v11
	v_exp_f32_e32 v235, v235
	v_exp_f32_e32 v236, v236
	v_exp_f32_e32 v237, v237
	v_exp_f32_e32 v238, v238
	v_exp_f32_e32 v239, v239
	v_exp_f32_e32 v240, v240
	v_exp_f32_e32 v241, v241
	v_exp_f32_e32 v242, v242
	v_add_f32_e32 v235, 1.0, v235
	v_add_f32_e32 v236, 1.0, v236
	v_add_f32_e32 v237, 1.0, v237
	v_add_f32_e32 v238, 1.0, v238
	v_add_f32_e32 v239, 1.0, v239
	v_add_f32_e32 v240, 1.0, v240
	v_add_f32_e32 v241, 1.0, v241
	v_add_f32_e32 v242, 1.0, v242
	v_rcp_f32_e32 v235, v235
	v_rcp_f32_e32 v236, v236
	v_rcp_f32_e32 v237, v237
	v_rcp_f32_e32 v238, v238
	v_rcp_f32_e32 v239, v239
	v_rcp_f32_e32 v240, v240
	v_rcp_f32_e32 v241, v241
	v_rcp_f32_e32 v242, v242
	s_waitcnt vmcnt(9)
	v_lshlrev_b32_e32 v160, 16, v92
	v_lshlrev_b32_e32 v161, 16, v88
	v_mul_f32_e32 v235, v235, v160
	v_mul_f32_e32 v235, v235, v161
	v_and_b32_e32 v160, 0xffff0000, v92
	v_and_b32_e32 v161, 0xffff0000, v88
	v_mul_f32_e32 v236, v236, v160
	v_mul_f32_e32 v236, v236, v161
	v_cvt_pk_bf16_f32 v244, v235, v236
	v_lshlrev_b32_e32 v160, 16, v93
	v_lshlrev_b32_e32 v161, 16, v89
	v_mul_f32_e32 v237, v237, v160
	v_mul_f32_e32 v237, v237, v161
	v_and_b32_e32 v160, 0xffff0000, v93
	v_and_b32_e32 v161, 0xffff0000, v89
	v_mul_f32_e32 v238, v238, v160
	v_mul_f32_e32 v238, v238, v161
	v_cvt_pk_bf16_f32 v245, v237, v238
	v_lshlrev_b32_e32 v160, 16, v94
	v_lshlrev_b32_e32 v161, 16, v90
	v_mul_f32_e32 v239, v239, v160
	v_mul_f32_e32 v239, v239, v161
	v_and_b32_e32 v160, 0xffff0000, v94
	v_and_b32_e32 v161, 0xffff0000, v90
	v_mul_f32_e32 v240, v240, v160
	v_mul_f32_e32 v240, v240, v161
	v_cvt_pk_bf16_f32 v246, v239, v240
	v_lshlrev_b32_e32 v160, 16, v95
	v_lshlrev_b32_e32 v161, 16, v91
	v_mul_f32_e32 v241, v241, v160
	v_mul_f32_e32 v241, v241, v161
	v_and_b32_e32 v160, 0xffff0000, v95
	v_and_b32_e32 v161, 0xffff0000, v91
	v_mul_f32_e32 v242, v242, v160
	v_mul_f32_e32 v242, v242, v161
	v_cvt_pk_bf16_f32 v247, v241, v242
	global_store_dwordx4 v255, v[244:247], s[70:71]
	v_add_f32_e32 v4, v4, v64
	v_add_f32_e32 v5, v5, v65
	v_add_f32_e32 v6, v6, v66
	v_add_f32_e32 v7, v7, v67
	v_add_f32_e32 v0, v0, v68
	v_add_f32_e32 v1, v1, v69
	v_add_f32_e32 v2, v2, v70
	v_add_f32_e32 v3, v3, v71
	v_mul_f32_e32 v235, 0xbfb8aa3b, v4
	v_mul_f32_e32 v236, 0xbfb8aa3b, v5
	v_mul_f32_e32 v237, 0xbfb8aa3b, v6
	v_mul_f32_e32 v238, 0xbfb8aa3b, v7
	v_mul_f32_e32 v239, 0xbfb8aa3b, v0
	v_mul_f32_e32 v240, 0xbfb8aa3b, v1
	v_mul_f32_e32 v241, 0xbfb8aa3b, v2
	v_mul_f32_e32 v242, 0xbfb8aa3b, v3
	v_exp_f32_e32 v235, v235
	v_exp_f32_e32 v236, v236
	v_exp_f32_e32 v237, v237
	v_exp_f32_e32 v238, v238
	v_exp_f32_e32 v239, v239
	v_exp_f32_e32 v240, v240
	v_exp_f32_e32 v241, v241
	v_exp_f32_e32 v242, v242
	v_add_f32_e32 v235, 1.0, v235
	v_add_f32_e32 v236, 1.0, v236
	v_add_f32_e32 v237, 1.0, v237
	v_add_f32_e32 v238, 1.0, v238
	v_add_f32_e32 v239, 1.0, v239
	v_add_f32_e32 v240, 1.0, v240
	v_add_f32_e32 v241, 1.0, v241
	v_add_f32_e32 v242, 1.0, v242
	v_rcp_f32_e32 v235, v235
	v_rcp_f32_e32 v236, v236
	v_rcp_f32_e32 v237, v237
	v_rcp_f32_e32 v238, v238
	v_rcp_f32_e32 v239, v239
	v_rcp_f32_e32 v240, v240
	v_rcp_f32_e32 v241, v241
	v_rcp_f32_e32 v242, v242
	s_waitcnt vmcnt(7)
	v_lshlrev_b32_e32 v160, 16, v84
	v_lshlrev_b32_e32 v161, 16, v80
	v_mul_f32_e32 v235, v235, v160
	v_mul_f32_e32 v235, v235, v161
	v_and_b32_e32 v160, 0xffff0000, v84
	v_and_b32_e32 v161, 0xffff0000, v80
	v_mul_f32_e32 v236, v236, v160
	v_mul_f32_e32 v236, v236, v161
	v_cvt_pk_bf16_f32 v248, v235, v236
	v_lshlrev_b32_e32 v160, 16, v85
	v_lshlrev_b32_e32 v161, 16, v81
	v_mul_f32_e32 v237, v237, v160
	v_mul_f32_e32 v237, v237, v161
	v_and_b32_e32 v160, 0xffff0000, v85
	v_and_b32_e32 v161, 0xffff0000, v81
	v_mul_f32_e32 v238, v238, v160
	v_mul_f32_e32 v238, v238, v161
	v_cvt_pk_bf16_f32 v249, v237, v238
	v_lshlrev_b32_e32 v160, 16, v86
	v_lshlrev_b32_e32 v161, 16, v82
	v_mul_f32_e32 v239, v239, v160
	v_mul_f32_e32 v239, v239, v161
	v_and_b32_e32 v160, 0xffff0000, v86
	v_and_b32_e32 v161, 0xffff0000, v82
	v_mul_f32_e32 v240, v240, v160
	v_mul_f32_e32 v240, v240, v161
	v_cvt_pk_bf16_f32 v250, v239, v240
	v_lshlrev_b32_e32 v160, 16, v87
	v_lshlrev_b32_e32 v161, 16, v83
	v_mul_f32_e32 v241, v241, v160
	v_mul_f32_e32 v241, v241, v161
	v_and_b32_e32 v160, 0xffff0000, v87
	v_and_b32_e32 v161, 0xffff0000, v83
	v_mul_f32_e32 v242, v242, v160
	v_mul_f32_e32 v242, v242, v161
	v_cvt_pk_bf16_f32 v251, v241, v242
	global_store_dwordx4 v255, v[248:251], s[70:71] offset:256
	s_cbranch_vccnz .LBB0_715
	s_andn2_b64 vcc, exec, s[8:9]
	s_cbranch_vccnz .LBB0_714
	s_barrier
	s_branch .LBB0_714
